# skinny GEMM epilogue (xq, up): folded-norm vector loads hoisted next to the statistics loads
# baseline (speedup 1.0000x reference)
; #define LAS __attribute__((address_space(3)))
; template <int KSPLIT, class F>
; __device__ __forceinline__ void skinny_gemm(const bf16_t* A, const bf16_t* Bt, int N, int K, const F& f, LAS unsigned char* lds, int bx, int G, int wave) {
;     ...
;     for (int t = bx; t < ntiles; t += G) {
;         const int rg = t % RG, n0 = (t / RG) * 16;
;         const int mt = rg * MTW + (wave % MTW), kq = wave / MTW;
;         const bf16_t* ap = A + (size_t)(MP + 16 * mt + fr) * K + kq * klen + 8 * fq;
;         const bf16_t* bp = Bt + (size_t)(n0 + fr) * K + kq * klen + 8 * fq;
;         f32x4 acc = (f32x4){0.f, 0.f, 0.f, 0.f};
; #pragma unroll 16
;         for (int k = 0; k < klen; k += 32) {
;             const bf16x8 af = *(const bf16x8*)(ap + k), bf = *(const bf16x8*)(bp + k);
;             acc = __builtin_amdgcn_mfma_f32_16x16x32_bf16(bf, af, acc, 0, 0, 0);
;         }
;         if (KSPLIT > 1) {
;             __syncthreads();
;             *(LAS f32x4*)(lds + wave * 1024 + lane * 16) = acc;
;             __syncthreads();
;             if (kq == 0) {
.LBB0_2033:
	s_ashr_i32 s1, s0, 31
	s_lshr_b32 s1, s1, 30
	s_add_i32 s1, s0, s1
	s_ashr_i32 s2, s1, 2
	s_lshl_b32 s1, s2, 4
	s_lshl_b32 s2, s2, 7
	v_subrev_u32_e32 v16, s2, v19
	v_add_u32_e32 v4, 0x4000, v16
	v_mov_b32_e32 v5, v2
	v_lshlrev_b64 v[12:13], 11, v[4:5]
	v_or_b32_e32 v4, s1, v3
	v_ashrrev_i32_e32 v5, 31, v4
	v_lshl_add_u64 v[14:15], v[0:1], 0, v[12:13]
	v_lshlrev_b64 v[4:5], 11, v[4:5]
	v_lshl_add_u64 v[30:31], v[8:9], 0, v[4:5]
	v_readlane_b32 s8, v253, 39
	v_readlane_b32 s9, v253, 40
	s_andn2_b64 vcc, exec, s[8:9]
	v_readlane_b32 s100, v251, 60
	s_mul_i32 s100, s100, 0x3000
	s_add_i32 s100, s100, 0x2000
	v_lshrrev_b32_e32 v202, 2, v219
	v_and_b32_e32 v203, 15, v219
	v_lshrrev_b32_e32 v201, 4, v219
	v_sub_u32_e32 v202, v202, v203
	v_lshlrev_b32_e32 v202, 11, v202
	v_and_b32_e32 v204, 3, v219
	v_xor_b32_e32 v204, v204, v201
	v_sub_u32_e32 v204, v204, v201
	v_lshl_add_u32 v202, v204, 4, v202
	v_lshrrev_b32_e32 v204, 2, v203
	v_xor_b32_e32 v204, v204, v201
	v_lshlrev_b32_e32 v200, 6, v203
	v_lshl_add_u32 v200, v204, 4, v200
	v_add_u32_e32 v200, s100, v200
	v_ashrrev_i32_e32 v203, 31, v202
	v_lshl_add_u64 v[196:197], v[202:203], 0, v[14:15]
	v_lshl_add_u64 v[198:199], v[202:203], 0, v[30:31]
	s_add_i32 m0, s100, 0
	s_nop 0
	global_load_lds_dwordx4 v[196:197], off
	s_add_i32 m0, s100, 1024
	s_nop 0
	global_load_lds_dwordx4 v[198:199], off
	s_add_i32 m0, s100, 1984
	s_nop 0
	global_load_lds_dwordx4 v[196:197], off offset:64
	s_add_i32 m0, s100, 3008
	s_nop 0
	global_load_lds_dwordx4 v[198:199], off offset:64
	s_add_i32 m0, s100, 3968
	s_nop 0
	global_load_lds_dwordx4 v[196:197], off offset:128
	s_add_i32 m0, s100, 4992
	s_nop 0
	global_load_lds_dwordx4 v[198:199], off offset:128
	s_add_i32 m0, s100, 5952
	s_nop 0
	global_load_lds_dwordx4 v[196:197], off offset:192
	s_add_i32 m0, s100, 6976
	s_nop 0
	global_load_lds_dwordx4 v[198:199], off offset:192
	s_add_i32 m0, s100, 7936
	s_nop 0
	global_load_lds_dwordx4 v[196:197], off offset:256
	s_add_i32 m0, s100, 8960
	s_nop 0
	global_load_lds_dwordx4 v[198:199], off offset:256
	s_add_i32 m0, s100, 9920
	s_nop 0
	global_load_lds_dwordx4 v[196:197], off offset:320
	s_add_i32 m0, s100, 10944
	s_nop 0
	global_load_lds_dwordx4 v[198:199], off offset:320
	s_waitcnt vmcnt(10)
	ds_read_b128 v[180:183], v200 offset:0
	ds_read_b128 v[184:187], v200 offset:1024
	s_waitcnt vmcnt(8)
	ds_read_b128 v[188:191], v200 offset:2048
	ds_read_b128 v[192:195], v200 offset:3072
	s_waitcnt lgkmcnt(2)
	v_mfma_f32_16x16x32_bf16 v[4:7], v[184:187], v[180:183], 0
	s_add_i32 m0, s100, -384
	s_nop 0
	global_load_lds_dwordx4 v[196:197], off offset:384
	s_add_i32 m0, s100, 640
	s_nop 0
	global_load_lds_dwordx4 v[198:199], off offset:384
	s_waitcnt vmcnt(8)
	ds_read_b128 v[180:183], v200 offset:4096
	ds_read_b128 v[184:187], v200 offset:5120
	s_waitcnt lgkmcnt(2)
	v_mfma_f32_16x16x32_bf16 v[4:7], v[192:195], v[188:191], v[4:7]
	s_add_i32 m0, s100, 1600
	s_nop 0
	global_load_lds_dwordx4 v[196:197], off offset:448
	s_add_i32 m0, s100, 2624
	s_nop 0
	global_load_lds_dwordx4 v[198:199], off offset:448
	s_waitcnt vmcnt(8)
	ds_read_b128 v[188:191], v200 offset:6144
	ds_read_b128 v[192:195], v200 offset:7168
	s_waitcnt lgkmcnt(2)
	v_mfma_f32_16x16x32_bf16 v[4:7], v[184:187], v[180:183], v[4:7]
	s_waitcnt vmcnt(6)
	ds_read_b128 v[180:183], v200 offset:8192
	ds_read_b128 v[184:187], v200 offset:9216
	s_waitcnt lgkmcnt(2)
	v_mfma_f32_16x16x32_bf16 v[4:7], v[192:195], v[188:191], v[4:7]
	s_waitcnt vmcnt(4)
	ds_read_b128 v[188:191], v200 offset:10240
	ds_read_b128 v[192:195], v200 offset:11264
	s_waitcnt lgkmcnt(2)
	v_mfma_f32_16x16x32_bf16 v[4:7], v[184:187], v[180:183], v[4:7]
	s_waitcnt vmcnt(2)
	ds_read_b128 v[180:183], v200 offset:0
	ds_read_b128 v[184:187], v200 offset:1024
	s_waitcnt lgkmcnt(2)
	v_mfma_f32_16x16x32_bf16 v[4:7], v[192:195], v[188:191], v[4:7]
	s_waitcnt vmcnt(0)
	ds_read_b128 v[188:191], v200 offset:2048
	ds_read_b128 v[192:195], v200 offset:3072
	s_waitcnt lgkmcnt(2)
	v_mfma_f32_16x16x32_bf16 v[4:7], v[184:187], v[180:183], v[4:7]
	s_waitcnt lgkmcnt(0)
	s_barrier
	v_mfma_f32_16x16x32_bf16 v[4:7], v[192:195], v[188:191], v[4:7]
	s_nop 7
	ds_write_b128 v20, v[4:7]
	s_waitcnt lgkmcnt(0)
	s_barrier
; __device__ __forceinline__ void stats_sk(const float* sts, int row, int fq, float& mu, float& rs) {
;     const f32x4* p = (const f32x4*)(sts + (size_t)(row - MP) * 128 + fq * 32);
;     float s1 = 0.f, s2 = 0.f;
; #pragma unroll
;     for (int i = 0; i < 8; ++i) { const f32x4 a = p[i]; s1 += a.x + a.z; s2 += a.y + a.w; }
;     s1 += __shfl_xor(s1, 16); s2 += __shfl_xor(s2, 16); s1 += __shfl_xor(s1, 32); s2 += __shfl_xor(s2, 32);
;     mu = s1 * (1.f / DM); rs = __builtin_amdgcn_rsqf(fmaxf(s2 * (1.f / DM) - mu * mu, 0.f) + LN_EPS);
;     __device__ __forceinline__ void sk(int row, int col, f32x4 v, int fq) const {
;         if (fold) { float mu, rs; stats_sk(sts, row, fq, mu, rs); const f32x4 c1v = *(const f32x4*)(c1 + col), c2v = *(const f32x4*)(c2 + col); v = (v - c1v * mu) * rs + c2v; }
;         float d1 = 0.f, d2 = 0.f; f(row, col, v, fq, d1, d2);
	s_cbranch_vccnz .LBB0_2032
	ds_read_b128 v[22:25], v20 offset:2048
	v_ashrrev_i32_e32 v17, 31, v16
	v_lshlrev_b64 v[16:17], 9, v[16:17]
	v_lshl_add_u64 v[16:17], v[10:11], 0, v[16:17]
	v_readlane_b32 s8, v252, 19
	s_waitcnt lgkmcnt(0)
	v_pk_add_f32 v[14:15], v[6:7], v[24:25]
	v_pk_add_f32 v[22:23], v[4:5], v[22:23]
	ds_read_b128 v[4:7], v20 offset:4096
	v_readlane_b32 s9, v252, 20
	s_waitcnt lgkmcnt(0)
	v_pk_add_f32 v[14:15], v[14:15], v[6:7]
	v_pk_add_f32 v[22:23], v[22:23], v[4:5]
	ds_read_b128 v[4:7], v20 offset:6144
	v_lshl_add_u64 v[12:13], s[8:9], 0, v[12:13]
	s_waitcnt lgkmcnt(0)
	v_pk_add_f32 v[6:7], v[14:15], v[6:7]
	v_pk_add_f32 v[14:15], v[22:23], v[4:5]
	global_load_dwordx4 v[22:25], v[16:17], off offset:48
	global_load_dwordx4 v[26:29], v[16:17], off offset:32
	global_load_dwordx4 v[30:33], v[16:17], off offset:16
	global_load_dwordx4 v[34:37], v[16:17], off
	global_load_dwordx4 v[38:41], v[16:17], off offset:112
	global_load_dwordx4 v[42:45], v[16:17], off offset:96
	global_load_dwordx4 v[46:49], v[16:17], off offset:80
	global_load_dwordx4 v[50:53], v[16:17], off offset:64
	v_add_u32_e32 v192, s1, v18
	v_ashrrev_i32_e32 v193, 31, v192
	v_lshlrev_b64 v[192:193], 2, v[192:193]
	v_lshl_add_u64 v[184:185], s[42:43], 0, v[192:193]
	v_lshl_add_u64 v[188:189], s[46:47], 0, v[192:193]
	global_load_dwordx4 v[184:187], v[184:185], off
	s_nop 0
	global_load_dwordx4 v[188:191], v[188:189], off
	v_and_b32_e32 v16, 64, v219
	v_xor_b32_e32 v5, 16, v219
	v_add_u32_e32 v16, 64, v16
	v_cmp_lt_i32_e32 vcc, v5, v16
	v_xor_b32_e32 v17, 32, v219
	v_add_u32_e32 v4, s1, v18
	v_cndmask_b32_e32 v5, v219, v5, vcc
	v_cmp_lt_i32_e32 vcc, v17, v16
	v_lshlrev_b32_e32 v5, 2, v5
	s_waitcnt vmcnt(9)
	v_pk_add_f32 v[22:23], v[22:23], v[24:25]
	v_cndmask_b32_e32 v16, v219, v17, vcc
	v_lshlrev_b32_e32 v21, 2, v16
	s_waitcnt vmcnt(6)
	v_pk_add_f32 v[16:17], v[34:35], v[36:37]
	v_pk_add_f32 v[30:31], v[30:31], v[32:33]
	v_pk_add_f32 v[16:17], v[16:17], 0 op_sel_hi:[1,0]
	v_pk_add_f32 v[26:27], v[26:27], v[28:29]
	v_pk_add_f32 v[16:17], v[16:17], v[30:31]
	s_nop 0
	v_pk_add_f32 v[16:17], v[16:17], v[26:27]
	s_nop 0
	v_pk_add_f32 v[16:17], v[16:17], v[22:23]
	s_waitcnt vmcnt(2)
	v_pk_add_f32 v[22:23], v[50:51], v[52:53]
	s_nop 0
	v_pk_add_f32 v[16:17], v[16:17], v[22:23]
	v_pk_add_f32 v[22:23], v[46:47], v[48:49]
	s_nop 0
	v_pk_add_f32 v[16:17], v[16:17], v[22:23]
	v_pk_add_f32 v[22:23], v[42:43], v[44:45]
	s_nop 0
	v_pk_add_f32 v[16:17], v[16:17], v[22:23]
	v_pk_add_f32 v[22:23], v[38:39], v[40:41]
	s_nop 0
	v_pk_add_f32 v[16:17], v[16:17], v[22:23]
	ds_bpermute_b32 v22, v5, v16
	ds_bpermute_b32 v23, v5, v17
	s_waitcnt lgkmcnt(0)
	v_pk_add_f32 v[16:17], v[16:17], v[22:23]
	ds_bpermute_b32 v22, v21, v16
	ds_bpermute_b32 v23, v21, v17
	s_waitcnt lgkmcnt(0)
	v_pk_add_f32 v[16:17], v[16:17], v[22:23]
	s_nop 0
	v_pk_mul_f32 v[16:17], v[16:17], s[82:83] op_sel_hi:[1,0]
	s_nop 0
	v_fma_f32 v5, -v16, v16, v17
	v_max_f32_e32 v5, 0, v5
	v_add_f32_e32 v5, 0x3727c5ac, v5
	v_rsq_f32_e32 v30, v5
	v_ashrrev_i32_e32 v5, 31, v4
	v_lshlrev_b64 v[26:27], 2, v[4:5]
	v_lshl_add_u64 v[22:23], s[42:43], 0, v[26:27]
	s_waitcnt vmcnt(0)
	v_mov_b32_e32 v22, v184
	v_mov_b32_e32 v23, v185
	v_mov_b32_e32 v24, v186
	v_mov_b32_e32 v25, v187
	v_lshl_add_u64 v[26:27], s[46:47], 0, v[26:27]
	v_mov_b32_e32 v26, v188
	v_mov_b32_e32 v27, v189
	v_mov_b32_e32 v28, v190
	v_mov_b32_e32 v29, v191
	v_lshl_add_u64 v[4:5], v[4:5], 1, v[12:13]
	s_waitcnt vmcnt(1)
	v_xor_b32_e32 v25, 0x80000000, v25
	v_xor_b32_e32 v24, 0x80000000, v24
	v_pk_fma_f32 v[6:7], v[24:25], v[16:17], v[6:7] op_sel_hi:[1,0,1]
	v_pk_fma_f32 v[14:15], v[22:23], v[16:17], v[14:15] op_sel_hi:[1,0,1] neg_lo:[1,0,0] neg_hi:[1,0,0]
	s_waitcnt vmcnt(0)
	v_pk_fma_f32 v[6:7], v[6:7], v[30:31], v[28:29] op_sel_hi:[1,0,1]
	v_pk_fma_f32 v[14:15], v[14:15], v[30:31], v[26:27] op_sel_hi:[1,0,1]
	v_pk_mul_f32 v[16:17], v[6:7], s[84:85] op_sel_hi:[1,0]
	v_pk_mul_f32 v[6:7], v[14:15], s[84:85] op_sel_hi:[1,0]
	s_nop 0
	v_cvt_pk_bf16_f32 v6, v6, v7
	v_cvt_pk_bf16_f32 v7, v16, v17
	global_store_dwordx2 v[4:5], v[6:7], off
	s_branch .LBB0_2032

; template <int KSPLIT, class F>
; __device__ __forceinline__ void skinny_gemm(const bf16_t* A, const bf16_t* Bt, int N, int K, const F& f, LAS unsigned char* lds, int bx, int G, int wave) {
;     ...
;         const bf16_t* ap = A + (size_t)(MP + 16 * mt + fr) * K + kq * klen + 8 * fq;
;         const bf16_t* bp = Bt + (size_t)(n0 + fr) * K + kq * klen + 8 * fq;
;         f32x4 acc = (f32x4){0.f, 0.f, 0.f, 0.f};
; #pragma unroll 16
;         for (int k = 0; k < klen; k += 32) {
;             const bf16x8 af = *(const bf16x8*)(ap + k), bf = *(const bf16x8*)(bp + k);
;             acc = __builtin_amdgcn_mfma_f32_16x16x32_bf16(bf, af, acc, 0, 0, 0);
;         }
.LBB0_2306:
	v_readlane_b32 s100, v251, 60
	s_mul_i32 s100, s100, 0x3000
	s_add_i32 s100, s100, 0x2000
	v_lshrrev_b32_e32 v202, 2, v219
	v_and_b32_e32 v203, 15, v219
	v_lshrrev_b32_e32 v201, 4, v219
	v_sub_u32_e32 v202, v202, v203
	v_lshlrev_b32_e32 v202, 11, v202
	v_and_b32_e32 v204, 3, v219
	v_xor_b32_e32 v204, v204, v201
	v_sub_u32_e32 v204, v204, v201
	v_lshl_add_u32 v202, v204, 4, v202
	v_lshrrev_b32_e32 v204, 2, v203
	v_xor_b32_e32 v204, v204, v201
	v_lshlrev_b32_e32 v200, 6, v203
	v_lshl_add_u32 v200, v204, 4, v200
	v_add_u32_e32 v200, s100, v200
	v_ashrrev_i32_e32 v203, 31, v202
	v_lshl_add_u64 v[196:197], v[202:203], 0, v[18:19]
	v_lshl_add_u64 v[198:199], v[202:203], 0, v[16:17]
	s_add_i32 m0, s100, 512
	s_nop 0
	global_load_lds_dwordx4 v[196:197], off offset:-512
	s_add_i32 m0, s100, 1536
	s_nop 0
	global_load_lds_dwordx4 v[198:199], off offset:-512
	s_add_i32 m0, s100, 2496
	s_nop 0
	global_load_lds_dwordx4 v[196:197], off offset:-448
	s_add_i32 m0, s100, 3520
	s_nop 0
	global_load_lds_dwordx4 v[198:199], off offset:-448
	s_add_i32 m0, s100, 4480
	s_nop 0
	global_load_lds_dwordx4 v[196:197], off offset:-384
	s_add_i32 m0, s100, 5504
	s_nop 0
	global_load_lds_dwordx4 v[198:199], off offset:-384
	s_add_i32 m0, s100, 6464
	s_nop 0
	global_load_lds_dwordx4 v[196:197], off offset:-320
	s_add_i32 m0, s100, 7488
	s_nop 0
	global_load_lds_dwordx4 v[198:199], off offset:-320
	s_add_i32 m0, s100, 8448
	s_nop 0
	global_load_lds_dwordx4 v[196:197], off offset:-256
	s_add_i32 m0, s100, 9472
	s_nop 0
	global_load_lds_dwordx4 v[198:199], off offset:-256
	s_add_i32 m0, s100, 10432
	s_nop 0
	global_load_lds_dwordx4 v[196:197], off offset:-192
	s_add_i32 m0, s100, 11456
	s_nop 0
	global_load_lds_dwordx4 v[198:199], off offset:-192
	s_waitcnt vmcnt(10)
	ds_read_b128 v[180:183], v200 offset:0
	ds_read_b128 v[184:187], v200 offset:1024
	s_waitcnt vmcnt(8)
	ds_read_b128 v[188:191], v200 offset:2048
	ds_read_b128 v[192:195], v200 offset:3072
	s_waitcnt lgkmcnt(2)
	v_mfma_f32_16x16x32_bf16 v[4:7], v[184:187], v[180:183], v[4:7]
	s_add_i32 m0, s100, 128
	s_nop 0
	global_load_lds_dwordx4 v[196:197], off offset:-128
	s_add_i32 m0, s100, 1152
	s_nop 0
	global_load_lds_dwordx4 v[198:199], off offset:-128
	s_waitcnt vmcnt(8)
	ds_read_b128 v[180:183], v200 offset:4096
	ds_read_b128 v[184:187], v200 offset:5120
	s_waitcnt lgkmcnt(2)
	v_mfma_f32_16x16x32_bf16 v[4:7], v[192:195], v[188:191], v[4:7]
	s_add_i32 m0, s100, 2112
	s_nop 0
	global_load_lds_dwordx4 v[196:197], off offset:-64
	s_add_i32 m0, s100, 3136
	s_nop 0
	global_load_lds_dwordx4 v[198:199], off offset:-64
	s_waitcnt vmcnt(8)
	ds_read_b128 v[188:191], v200 offset:6144
	ds_read_b128 v[192:195], v200 offset:7168
	s_waitcnt lgkmcnt(2)
	v_mfma_f32_16x16x32_bf16 v[4:7], v[184:187], v[180:183], v[4:7]
	s_add_i32 m0, s100, 4096
	s_nop 0
	global_load_lds_dwordx4 v[196:197], off
	s_add_i32 m0, s100, 5120
	s_nop 0
	global_load_lds_dwordx4 v[198:199], off
	s_waitcnt vmcnt(8)
	ds_read_b128 v[180:183], v200 offset:8192
	ds_read_b128 v[184:187], v200 offset:9216
	s_waitcnt lgkmcnt(2)
	v_mfma_f32_16x16x32_bf16 v[4:7], v[192:195], v[188:191], v[4:7]
	s_add_i32 m0, s100, 6080
	s_nop 0
	global_load_lds_dwordx4 v[196:197], off offset:64
	s_add_i32 m0, s100, 7104
	s_nop 0
	global_load_lds_dwordx4 v[198:199], off offset:64
	s_waitcnt vmcnt(8)
	ds_read_b128 v[188:191], v200 offset:10240
	ds_read_b128 v[192:195], v200 offset:11264
	s_waitcnt lgkmcnt(2)
	v_mfma_f32_16x16x32_bf16 v[4:7], v[184:187], v[180:183], v[4:7]
	s_add_i32 m0, s100, 8064
	s_nop 0
	global_load_lds_dwordx4 v[196:197], off offset:128
	s_add_i32 m0, s100, 9088
	s_nop 0
	global_load_lds_dwordx4 v[198:199], off offset:128
	s_waitcnt vmcnt(8)
	ds_read_b128 v[180:183], v200 offset:0
	ds_read_b128 v[184:187], v200 offset:1024
	s_waitcnt lgkmcnt(2)
	v_mfma_f32_16x16x32_bf16 v[4:7], v[192:195], v[188:191], v[4:7]
	s_add_i32 m0, s100, 10048
	s_nop 0
	global_load_lds_dwordx4 v[196:197], off offset:192
	s_add_i32 m0, s100, 11072
	s_nop 0
	global_load_lds_dwordx4 v[198:199], off offset:192
	s_waitcnt vmcnt(8)
	ds_read_b128 v[188:191], v200 offset:2048
	ds_read_b128 v[192:195], v200 offset:3072
	s_waitcnt lgkmcnt(2)
	v_mfma_f32_16x16x32_bf16 v[4:7], v[184:187], v[180:183], v[4:7]
	s_add_i32 m0, s100, -256
	s_nop 0
	global_load_lds_dwordx4 v[196:197], off offset:256
	s_add_i32 m0, s100, 768
	s_nop 0
	global_load_lds_dwordx4 v[198:199], off offset:256
	s_waitcnt vmcnt(8)
	ds_read_b128 v[180:183], v200 offset:4096
	ds_read_b128 v[184:187], v200 offset:5120
	s_waitcnt lgkmcnt(2)
	v_mfma_f32_16x16x32_bf16 v[4:7], v[192:195], v[188:191], v[4:7]
	s_add_i32 m0, s100, 1728
	s_nop 0
	global_load_lds_dwordx4 v[196:197], off offset:320
	s_add_i32 m0, s100, 2752
	s_nop 0
	global_load_lds_dwordx4 v[198:199], off offset:320
	s_waitcnt vmcnt(8)
	ds_read_b128 v[188:191], v200 offset:6144
	ds_read_b128 v[192:195], v200 offset:7168
	s_waitcnt lgkmcnt(2)
	v_mfma_f32_16x16x32_bf16 v[4:7], v[184:187], v[180:183], v[4:7]
	s_add_i32 m0, s100, 3712
	s_nop 0
	global_load_lds_dwordx4 v[196:197], off offset:384
	s_add_i32 m0, s100, 4736
	s_nop 0
	global_load_lds_dwordx4 v[198:199], off offset:384
	s_waitcnt vmcnt(8)
	ds_read_b128 v[180:183], v200 offset:8192
	ds_read_b128 v[184:187], v200 offset:9216
	s_waitcnt lgkmcnt(2)
	v_mfma_f32_16x16x32_bf16 v[4:7], v[192:195], v[188:191], v[4:7]
	s_add_i32 m0, s100, 5696
	s_nop 0
	global_load_lds_dwordx4 v[196:197], off offset:448
	s_add_i32 m0, s100, 6720
	s_nop 0
	global_load_lds_dwordx4 v[198:199], off offset:448
	s_waitcnt vmcnt(8)
	ds_read_b128 v[188:191], v200 offset:10240
	ds_read_b128 v[192:195], v200 offset:11264
	s_waitcnt lgkmcnt(2)
; template <int KSPLIT, class F>
; __device__ __forceinline__ void skinny_gemm(const bf16_t* A, const bf16_t* Bt, int N, int K, const F& f, LAS unsigned char* lds, int bx, int G, int wave) {
;     ...
; #pragma unroll 16
;         for (int k = 0; k < klen; k += 32) {
;             const bf16x8 af = *(const bf16x8*)(ap + k), bf = *(const bf16x8*)(bp + k);
;             acc = __builtin_amdgcn_mfma_f32_16x16x32_bf16(bf, af, acc, 0, 0, 0);
;         }
	v_mfma_f32_16x16x32_bf16 v[4:7], v[184:187], v[180:183], v[4:7]
	s_add_i32 m0, s100, 7680
	s_nop 0
	global_load_lds_dwordx4 v[196:197], off offset:512
	s_add_i32 m0, s100, 8704
	s_nop 0
	global_load_lds_dwordx4 v[198:199], off offset:512
	s_waitcnt vmcnt(8)
	ds_read_b128 v[180:183], v200 offset:0
	ds_read_b128 v[184:187], v200 offset:1024
	s_waitcnt lgkmcnt(2)
	v_mfma_f32_16x16x32_bf16 v[4:7], v[192:195], v[188:191], v[4:7]
	s_add_i32 m0, s100, 9664
	s_nop 0
	global_load_lds_dwordx4 v[196:197], off offset:576
	s_add_i32 m0, s100, 10688
	s_nop 0
	global_load_lds_dwordx4 v[198:199], off offset:576
	s_waitcnt vmcnt(8)
	ds_read_b128 v[188:191], v200 offset:2048
	ds_read_b128 v[192:195], v200 offset:3072
	s_waitcnt lgkmcnt(2)
	v_mfma_f32_16x16x32_bf16 v[4:7], v[184:187], v[180:183], v[4:7]
	s_add_i32 m0, s100, -640
	s_nop 0
	global_load_lds_dwordx4 v[196:197], off offset:640
	s_add_i32 m0, s100, 384
	s_nop 0
	global_load_lds_dwordx4 v[198:199], off offset:640
	s_waitcnt vmcnt(8)
	ds_read_b128 v[180:183], v200 offset:4096
	ds_read_b128 v[184:187], v200 offset:5120
	s_waitcnt lgkmcnt(2)
	v_mfma_f32_16x16x32_bf16 v[4:7], v[192:195], v[188:191], v[4:7]
	s_add_i32 m0, s100, 1344
	s_nop 0
	global_load_lds_dwordx4 v[196:197], off offset:704
	s_add_i32 m0, s100, 2368
	s_nop 0
	global_load_lds_dwordx4 v[198:199], off offset:704
	s_waitcnt vmcnt(8)
	ds_read_b128 v[188:191], v200 offset:6144
	ds_read_b128 v[192:195], v200 offset:7168
	s_waitcnt lgkmcnt(2)
	v_mfma_f32_16x16x32_bf16 v[4:7], v[184:187], v[180:183], v[4:7]
	s_add_i32 m0, s100, 3328
	s_nop 0
	global_load_lds_dwordx4 v[196:197], off offset:768
	s_add_i32 m0, s100, 4352
	s_nop 0
	global_load_lds_dwordx4 v[198:199], off offset:768
	s_waitcnt vmcnt(8)
	ds_read_b128 v[180:183], v200 offset:8192
	ds_read_b128 v[184:187], v200 offset:9216
	s_waitcnt lgkmcnt(2)
	v_mfma_f32_16x16x32_bf16 v[4:7], v[192:195], v[188:191], v[4:7]
	s_add_i32 m0, s100, 5312
	s_nop 0
	global_load_lds_dwordx4 v[196:197], off offset:832
	s_add_i32 m0, s100, 6336
	s_nop 0
	global_load_lds_dwordx4 v[198:199], off offset:832
	s_waitcnt vmcnt(8)
	ds_read_b128 v[188:191], v200 offset:10240
	ds_read_b128 v[192:195], v200 offset:11264
	s_waitcnt lgkmcnt(2)
	v_mfma_f32_16x16x32_bf16 v[4:7], v[184:187], v[180:183], v[4:7]
	s_add_i32 m0, s100, 7296
	s_nop 0
	global_load_lds_dwordx4 v[196:197], off offset:896
	s_add_i32 m0, s100, 8320
	s_nop 0
	global_load_lds_dwordx4 v[198:199], off offset:896
	s_waitcnt vmcnt(8)
	ds_read_b128 v[180:183], v200 offset:0
	ds_read_b128 v[184:187], v200 offset:1024
	s_waitcnt lgkmcnt(2)
	v_mfma_f32_16x16x32_bf16 v[4:7], v[192:195], v[188:191], v[4:7]
	s_add_i32 m0, s100, 9280
	s_nop 0
	global_load_lds_dwordx4 v[196:197], off offset:960
	s_add_i32 m0, s100, 10304
	s_nop 0
	global_load_lds_dwordx4 v[198:199], off offset:960
	s_waitcnt vmcnt(8)
	ds_read_b128 v[188:191], v200 offset:2048
	ds_read_b128 v[192:195], v200 offset:3072
	s_waitcnt lgkmcnt(2)
	v_mfma_f32_16x16x32_bf16 v[4:7], v[184:187], v[180:183], v[4:7]
	s_add_i32 m0, s100, -1024
	s_nop 0
	global_load_lds_dwordx4 v[196:197], off offset:1024
	s_add_i32 m0, s100, 0
	s_nop 0
	global_load_lds_dwordx4 v[198:199], off offset:1024
	s_waitcnt vmcnt(8)
	ds_read_b128 v[180:183], v200 offset:4096
	ds_read_b128 v[184:187], v200 offset:5120
	s_waitcnt lgkmcnt(2)
	v_mfma_f32_16x16x32_bf16 v[4:7], v[192:195], v[188:191], v[4:7]
	s_add_i32 m0, s100, 960
	s_nop 0
	global_load_lds_dwordx4 v[196:197], off offset:1088
	s_add_i32 m0, s100, 1984
	s_nop 0
	global_load_lds_dwordx4 v[198:199], off offset:1088
	s_waitcnt vmcnt(8)
	ds_read_b128 v[188:191], v200 offset:6144
	ds_read_b128 v[192:195], v200 offset:7168
	s_waitcnt lgkmcnt(2)
	v_mfma_f32_16x16x32_bf16 v[4:7], v[184:187], v[180:183], v[4:7]
	s_add_i32 m0, s100, 2944
	s_nop 0
	global_load_lds_dwordx4 v[196:197], off offset:1152
	s_add_i32 m0, s100, 3968
	s_nop 0
	global_load_lds_dwordx4 v[198:199], off offset:1152
	s_waitcnt vmcnt(8)
	ds_read_b128 v[180:183], v200 offset:8192
	ds_read_b128 v[184:187], v200 offset:9216
	s_waitcnt lgkmcnt(2)
	v_mfma_f32_16x16x32_bf16 v[4:7], v[192:195], v[188:191], v[4:7]
	s_add_i32 m0, s100, 4928
	s_nop 0
	global_load_lds_dwordx4 v[196:197], off offset:1216
	s_add_i32 m0, s100, 5952
	s_nop 0
	global_load_lds_dwordx4 v[198:199], off offset:1216
	s_waitcnt vmcnt(8)
	ds_read_b128 v[188:191], v200 offset:10240
	ds_read_b128 v[192:195], v200 offset:11264
	s_waitcnt lgkmcnt(2)
	v_mfma_f32_16x16x32_bf16 v[4:7], v[184:187], v[180:183], v[4:7]
	s_add_i32 m0, s100, 6912
	s_nop 0
	global_load_lds_dwordx4 v[196:197], off offset:1280
	s_add_i32 m0, s100, 7936
	s_nop 0
	global_load_lds_dwordx4 v[198:199], off offset:1280
	s_waitcnt vmcnt(8)
	ds_read_b128 v[180:183], v200 offset:0
	ds_read_b128 v[184:187], v200 offset:1024
	s_waitcnt lgkmcnt(2)
	v_mfma_f32_16x16x32_bf16 v[4:7], v[192:195], v[188:191], v[4:7]
	s_add_i32 m0, s100, 8896
	s_nop 0
	global_load_lds_dwordx4 v[196:197], off offset:1344
	s_add_i32 m0, s100, 9920
	s_nop 0
	global_load_lds_dwordx4 v[198:199], off offset:1344
	s_waitcnt vmcnt(8)
; __device__ __forceinline__ void stats_sk(const float* sts, int row, int fq, float& mu, float& rs) {
;     const f32x4* p = (const f32x4*)(sts + (size_t)(row - MP) * 128 + fq * 32);
;     float s1 = 0.f, s2 = 0.f;
; #pragma unroll
;     for (int i = 0; i < 8; ++i) { const f32x4 a = p[i]; s1 += a.x + a.z; s2 += a.y + a.w; }
;     s1 += __shfl_xor(s1, 16); s2 += __shfl_xor(s2, 16); s1 += __shfl_xor(s1, 32); s2 += __shfl_xor(s2, 32);
;     mu = s1 * (1.f / DM); rs = __builtin_amdgcn_rsqf(fmaxf(s2 * (1.f / DM) - mu * mu, 0.f) + LN_EPS);
; }
;     __device__ __forceinline__ void operator()(const f32x4 (&acc)[2][2][4][2], const pg8::Unit& u, int wr, int wc, int fr, int fq) const {
;         float mu[2][4], rs[2][4], ps1[2][4], ps2[2][4];
; #pragma unroll
;         for (int ai = 0; ai < 2; ++ai)
; #pragma unroll
;             for (int m = 0; m < 4; ++m) { ps1[ai][m] = 0.f; ps2[ai][m] = 0.f; mu[ai][m] = 0.f; rs[ai][m] = 1.f; if (fold) stats_main(stm, u.pm * 256 + ai * 128 + wr * 64 + m * 16 + fr, fq, mu[ai][m], rs[ai][m]); }
; #pragma unroll
;         for (int bj = 0; bj < 2; ++bj)
; #pragma unroll
;             for (int n = 0; n < 2; ++n) {
;                 const int col = u.pn * 256 + bj * 128 + wc * 32 + n * 16 + fq * 4;
;                 f32x4 c1v = (f32x4){0.f, 0.f, 0.f, 0.f}, c2v = c1v;
;                 if (fold) { c1v = *(const f32x4*)(c1 + col); c2v = *(const f32x4*)(c2 + col); }
; #pragma unroll
;                 for (int ai = 0; ai < 2; ++ai)
; template <int KSPLIT, class F>
; __device__ __forceinline__ void skinny_gemm(const bf16_t* A, const bf16_t* Bt, int N, int K, const F& f, LAS unsigned char* lds, int bx, int G, int wave) {
;     ...
; #pragma unroll 16
;         for (int k = 0; k < klen; k += 32) {
;             const bf16x8 af = *(const bf16x8*)(ap + k), bf = *(const bf16x8*)(bp + k);
;             acc = __builtin_amdgcn_mfma_f32_16x16x32_bf16(bf, af, acc, 0, 0, 0);
;         }
;         if (KSPLIT > 1) {
;             __syncthreads();
;             *(LAS f32x4*)(lds + wave * 1024 + lane * 16) = acc;
;             __syncthreads();
;             if (kq == 0) {
; #pragma unroll
;                 for (int q = 1; q < KSPLIT; ++q) acc = acc + *(const LAS f32x4*)(lds + (wave + q * MTW) * 1024 + lane * 16);
;                 f.sk(MP + 16 * mt + fr, n0 + 4 * fq, acc, fq);
;             }
;         } else f.sk(MP + 16 * mt + fr, n0 + 4 * fq, acc, fq);
	ds_read_b128 v[188:191], v200 offset:2048
	ds_read_b128 v[192:195], v200 offset:3072
	s_waitcnt lgkmcnt(2)
	v_mfma_f32_16x16x32_bf16 v[4:7], v[184:187], v[180:183], v[4:7]
	s_add_i32 m0, s100, -1408
	s_nop 0
	global_load_lds_dwordx4 v[196:197], off offset:1408
	s_add_i32 m0, s100, -384
	s_nop 0
	global_load_lds_dwordx4 v[198:199], off offset:1408
	s_waitcnt vmcnt(8)
	ds_read_b128 v[180:183], v200 offset:4096
	ds_read_b128 v[184:187], v200 offset:5120
	s_waitcnt lgkmcnt(2)
	v_mfma_f32_16x16x32_bf16 v[4:7], v[192:195], v[188:191], v[4:7]
	s_add_i32 m0, s100, 576
	s_nop 0
	global_load_lds_dwordx4 v[196:197], off offset:1472
	s_add_i32 m0, s100, 1600
	s_nop 0
	global_load_lds_dwordx4 v[198:199], off offset:1472
	s_waitcnt vmcnt(8)
	ds_read_b128 v[188:191], v200 offset:6144
	ds_read_b128 v[192:195], v200 offset:7168
	s_waitcnt lgkmcnt(2)
	v_mfma_f32_16x16x32_bf16 v[4:7], v[184:187], v[180:183], v[4:7]
	s_waitcnt vmcnt(6)
	ds_read_b128 v[180:183], v200 offset:8192
	ds_read_b128 v[184:187], v200 offset:9216
	s_waitcnt lgkmcnt(2)
	v_mfma_f32_16x16x32_bf16 v[4:7], v[192:195], v[188:191], v[4:7]
	s_waitcnt vmcnt(4)
	ds_read_b128 v[188:191], v200 offset:10240
	ds_read_b128 v[192:195], v200 offset:11264
	s_waitcnt lgkmcnt(2)
	v_mfma_f32_16x16x32_bf16 v[4:7], v[184:187], v[180:183], v[4:7]
	s_waitcnt vmcnt(2)
	ds_read_b128 v[180:183], v200 offset:0
	ds_read_b128 v[184:187], v200 offset:1024
	s_waitcnt lgkmcnt(2)
	v_mfma_f32_16x16x32_bf16 v[4:7], v[192:195], v[188:191], v[4:7]
	s_waitcnt vmcnt(0)
	ds_read_b128 v[188:191], v200 offset:2048
	ds_read_b128 v[192:195], v200 offset:3072
	s_waitcnt lgkmcnt(2)
	v_mfma_f32_16x16x32_bf16 v[4:7], v[184:187], v[180:183], v[4:7]
	s_waitcnt lgkmcnt(0)
	v_mfma_f32_16x16x32_bf16 v[4:7], v[192:195], v[188:191], v[4:7]
	s_nop 0
	global_load_dwordx4 v[16:19], v[0:1], off offset:48
	global_load_dwordx4 v[22:25], v[0:1], off offset:32
	global_load_dwordx4 v[26:29], v[0:1], off offset:16
	global_load_dwordx4 v[30:33], v[0:1], off
	global_load_dwordx4 v[34:37], v[0:1], off offset:112
	global_load_dwordx4 v[38:41], v[0:1], off offset:96
	global_load_dwordx4 v[42:45], v[0:1], off offset:80
	global_load_dwordx4 v[46:49], v[0:1], off offset:64
	v_lshl_add_u32 v192, s0, 4, v3
	v_ashrrev_i32_e32 v193, 31, v192
	v_lshlrev_b64 v[192:193], 2, v[192:193]
	v_lshl_add_u64 v[184:185], s[42:43], 0, v[192:193]
	v_lshl_add_u64 v[188:189], s[46:47], 0, v[192:193]
	global_load_dwordx4 v[184:187], v[184:185], off
	s_nop 0
	global_load_dwordx4 v[188:191], v[188:189], off
	v_lshl_add_u32 v50, s0, 4, v3
	v_ashrrev_i32_e32 v51, 31, v50
	s_add_i32 s0, s0, s26
	v_readlane_b32 s1, v254, 54
	s_cmpk_gt_i32 s0, 0xff
	s_waitcnt vmcnt(9)
	v_pk_add_f32 v[16:17], v[16:17], v[18:19]
	s_waitcnt vmcnt(8)
	v_pk_add_f32 v[22:23], v[22:23], v[24:25]
	s_waitcnt vmcnt(7)
	v_pk_add_f32 v[26:27], v[26:27], v[28:29]
	s_waitcnt vmcnt(6)
	v_pk_add_f32 v[30:31], v[30:31], v[32:33]
	v_add_u32_e32 v12, s1, v12
	v_pk_add_f32 v[30:31], v[30:31], 0 op_sel_hi:[1,0]
	s_waitcnt vmcnt(2)
	v_pk_add_f32 v[18:19], v[46:47], v[48:49]
	v_pk_add_f32 v[26:27], v[30:31], v[26:27]
	s_nop 0
	v_pk_add_f32 v[22:23], v[26:27], v[22:23]
	s_nop 0
	v_pk_add_f32 v[16:17], v[22:23], v[16:17]
	v_lshlrev_b64 v[22:23], 2, v[50:51]
	v_pk_add_f32 v[16:17], v[16:17], v[18:19]
	v_pk_add_f32 v[18:19], v[42:43], v[44:45]
	s_nop 0
	v_pk_add_f32 v[16:17], v[16:17], v[18:19]
	v_pk_add_f32 v[18:19], v[38:39], v[40:41]
	s_nop 0
	v_pk_add_f32 v[16:17], v[16:17], v[18:19]
	v_pk_add_f32 v[18:19], v[34:35], v[36:37]
	s_nop 0
	v_pk_add_f32 v[16:17], v[16:17], v[18:19]
	ds_bpermute_b32 v18, v20, v16
	ds_bpermute_b32 v19, v20, v17
	s_waitcnt lgkmcnt(0)
	v_pk_add_f32 v[16:17], v[16:17], v[18:19]
	ds_bpermute_b32 v18, v21, v16
	ds_bpermute_b32 v19, v21, v17
	s_waitcnt lgkmcnt(0)
	v_pk_add_f32 v[16:17], v[16:17], v[18:19]
	s_nop 0
	v_pk_mul_f32 v[26:27], v[16:17], s[82:83] op_sel_hi:[1,0]
	v_lshl_add_u64 v[16:17], s[42:43], 0, v[22:23]
	s_waitcnt vmcnt(0)
	v_mov_b32_e32 v16, v184
	v_mov_b32_e32 v17, v185
	v_mov_b32_e32 v18, v186
	v_mov_b32_e32 v19, v187
	v_lshl_add_u64 v[22:23], s[46:47], 0, v[22:23]
	v_mov_b32_e32 v22, v188
	v_mov_b32_e32 v23, v189
	v_mov_b32_e32 v24, v190
	v_mov_b32_e32 v25, v191
	v_fma_f32 v13, -v26, v26, v27
	v_max_f32_e32 v13, 0, v13
	v_add_f32_e32 v13, 0x3727c5ac, v13
	v_rsq_f32_e32 v28, v13
	s_waitcnt vmcnt(1)
	v_xor_b32_e32 v19, 0x80000000, v19
	v_xor_b32_e32 v18, 0x80000000, v18
	v_pk_fma_f32 v[6:7], v[18:19], v[26:27], v[6:7] op_sel_hi:[1,0,1]
	v_pk_fma_f32 v[4:5], v[16:17], v[26:27], v[4:5] op_sel_hi:[1,0,1] neg_lo:[1,0,0] neg_hi:[1,0,0]
	s_waitcnt vmcnt(0)
	v_pk_fma_f32 v[6:7], v[6:7], v[28:29], v[24:25] op_sel_hi:[1,0,1]
	v_pk_fma_f32 v[4:5], v[4:5], v[28:29], v[22:23] op_sel_hi:[1,0,1]
	v_max_f32_e32 v6, 0, v6
	v_max_f32_e32 v4, 0, v4
	v_max_f32_e32 v5, 0, v5
	v_max_f32_e32 v7, 0, v7
	v_pk_mul_f32 v[6:7], v[6:7], v[6:7]
	v_pk_mul_f32 v[4:5], v[4:5], v[4:5]
	s_nop 0
	v_cvt_pk_bf16_f32 v4, v4, v5
	v_cvt_pk_bf16_f32 v5, v6, v7
	v_lshl_add_u64 v[6:7], v[50:51], 1, v[8:9]
	global_store_dwordx2 v[6:7], v[4:5], off
	s_cbranch_scc0 .LBB0_2305
